# attention: K/V LDS-DMA issued in the first MFMA gaps of even steps
# speedup vs baseline: 1.1130x; 1.0037x over previous
.Lat_stab0_ret:
	v_mfma_f32_32x32x16_bf16 v[16:31], v[224:227], v[96:99], 0
	ds_read_b128 v[208:211], v244 offset:16384
	v_cvt_pk_bf16_f32 v112, v80, v81
	v_cvt_pk_bf16_f32 v113, v82, v83
	v_cvt_pk_bf16_f32 v114, v84, v85
	v_cvt_pk_bf16_f32 v115, v86, v87
	v_cvt_pk_bf16_f32 v116, v88, v89
	s_add_i32 m0, s83, 32768
	s_nop 0
	global_load_lds_dwordx4 v252, s[78:79]
	v_mfma_f32_32x32x16_bf16 v[16:31], v[228:231], v[100:103], v[16:31]
	ds_read_b128 v[212:215], v245 offset:16384
	v_cvt_pk_bf16_f32 v117, v90, v91
	v_cvt_pk_bf16_f32 v118, v92, v93
	v_cvt_pk_bf16_f32 v119, v94, v95
	v_exp_f32_e32 v64, v0
	v_exp_f32_e32 v65, v1
	global_load_lds_dwordx4 v253, s[78:79] offset:1024
	s_add_i32 m0, s83, 40960
	s_nop 0
	v_mfma_f32_32x32x16_bf16 v[16:31], v[232:235], v[104:107], v[16:31]
	ds_read_b128 v[216:219], v246 offset:16384
	v_exp_f32_e32 v66, v2
	v_add_f32_e32 v136, v64, v65
	v_exp_f32_e32 v67, v3
	v_add_f32_e32 v136, v66, v136
	v_exp_f32_e32 v68, v4
	global_load_lds_dwordx4 v254, s[80:81]
	s_add_u32 s78, s78, 0x2000
	s_addc_u32 s79, s79, 0
	v_mfma_f32_32x32x16_bf16 v[16:31], v[236:239], v[108:111], v[16:31]
	ds_read_b128 v[220:223], v247 offset:16384
	v_add_f32_e32 v136, v67, v136
	v_exp_f32_e32 v69, v5
	v_add_f32_e32 v136, v68, v136
	v_exp_f32_e32 v70, v6
	v_add_f32_e32 v136, v69, v136
	global_load_lds_dwordx4 v255, s[80:81] offset:1024
	s_add_u32 s80, s80, 0x80
	s_addc_u32 s81, s81, 0
	s_waitcnt lgkmcnt(4)
	v_mfma_f32_32x32x16_bf16 v[32:47], v[192:195], v[112:115], v[32:47]
	ds_read_b128 v[176:179], v248 offset:8192
	v_exp_f32_e32 v71, v7
	v_add_f32_e32 v136, v70, v136
	v_exp_f32_e32 v72, v8
	v_add_f32_e32 v136, v71, v136
	v_exp_f32_e32 v73, v9
	v_mfma_f32_32x32x16_bf16 v[48:63], v[196:199], v[112:115], v[48:63]
	ds_read_b128 v[180:183], v248 offset:12288
	v_add_f32_e32 v136, v72, v136
	v_exp_f32_e32 v74, v10
	v_add_f32_e32 v136, v73, v136
	v_exp_f32_e32 v75, v11
	v_add_f32_e32 v136, v74, v136
	v_mfma_f32_32x32x16_bf16 v[32:47], v[200:203], v[116:119], v[32:47]
	ds_read_b128 v[184:187], v249 offset:8192
	v_exp_f32_e32 v76, v12
	v_add_f32_e32 v136, v75, v136
	v_exp_f32_e32 v77, v13
	v_add_f32_e32 v136, v76, v136
	v_exp_f32_e32 v78, v14
	v_mfma_f32_32x32x16_bf16 v[48:63], v[240:243], v[116:119], v[48:63]
	ds_read_b128 v[188:191], v249 offset:12288
	v_add_f32_e32 v136, v77, v136
	v_exp_f32_e32 v79, v15
	v_add_f32_e32 v136, v78, v136
	s_nop 0
	v_add_f32_e32 v134, v79, v136
	v_cmp_nge_f32_e32 vcc, s65, v134
	v_cmp_gt_f32_e64 s[0:1], s72, v134
	s_or_b64 vcc, vcc, s[0:1]
	s_cbranch_vccnz .Lat_rare0

.Lat_stab2_ret:
	v_mfma_f32_32x32x16_bf16 v[16:31], v[224:227], v[96:99], 0
	ds_read_b128 v[208:211], v244 offset:32768
	v_cvt_pk_bf16_f32 v112, v80, v81
	v_cvt_pk_bf16_f32 v113, v82, v83
	v_cvt_pk_bf16_f32 v114, v84, v85
	v_cvt_pk_bf16_f32 v115, v86, v87
	v_cvt_pk_bf16_f32 v116, v88, v89
	s_add_i32 m0, s83, 49152
	s_nop 0
	global_load_lds_dwordx4 v252, s[78:79]
	v_mfma_f32_32x32x16_bf16 v[16:31], v[228:231], v[100:103], v[16:31]
	ds_read_b128 v[212:215], v245 offset:32768
	v_cvt_pk_bf16_f32 v117, v90, v91
	v_cvt_pk_bf16_f32 v118, v92, v93
	v_cvt_pk_bf16_f32 v119, v94, v95
	v_exp_f32_e32 v64, v0
	v_exp_f32_e32 v65, v1
	global_load_lds_dwordx4 v253, s[78:79] offset:1024
	s_add_i32 m0, s83, 57344
	s_nop 0
	v_mfma_f32_32x32x16_bf16 v[16:31], v[232:235], v[104:107], v[16:31]
	ds_read_b128 v[216:219], v246 offset:32768
	v_exp_f32_e32 v66, v2
	v_add_f32_e32 v136, v64, v65
	v_exp_f32_e32 v67, v3
	v_add_f32_e32 v136, v66, v136
	v_exp_f32_e32 v68, v4
	global_load_lds_dwordx4 v254, s[80:81]
	s_add_u32 s78, s78, 0x2000
	s_addc_u32 s79, s79, 0
	v_mfma_f32_32x32x16_bf16 v[16:31], v[236:239], v[108:111], v[16:31]
	ds_read_b128 v[220:223], v247 offset:32768
	v_add_f32_e32 v136, v67, v136
	v_exp_f32_e32 v69, v5
	v_add_f32_e32 v136, v68, v136
	v_exp_f32_e32 v70, v6
	v_add_f32_e32 v136, v69, v136
	global_load_lds_dwordx4 v255, s[80:81] offset:1024
	s_add_u32 s80, s80, 0x80
	s_addc_u32 s81, s81, 0
	s_waitcnt lgkmcnt(4)
	v_mfma_f32_32x32x16_bf16 v[32:47], v[192:195], v[112:115], v[32:47]
	ds_read_b128 v[176:179], v248 offset:24576
	v_exp_f32_e32 v71, v7
	v_add_f32_e32 v136, v70, v136
	v_exp_f32_e32 v72, v8
	v_add_f32_e32 v136, v71, v136
	v_exp_f32_e32 v73, v9
	v_mfma_f32_32x32x16_bf16 v[48:63], v[196:199], v[112:115], v[48:63]
	ds_read_b128 v[180:183], v248 offset:28672
	v_add_f32_e32 v136, v72, v136
	v_exp_f32_e32 v74, v10
	v_add_f32_e32 v136, v73, v136
	v_exp_f32_e32 v75, v11
	v_add_f32_e32 v136, v74, v136
	v_mfma_f32_32x32x16_bf16 v[32:47], v[200:203], v[116:119], v[32:47]
	ds_read_b128 v[184:187], v249 offset:24576
	v_exp_f32_e32 v76, v12
	v_add_f32_e32 v136, v75, v136
	v_exp_f32_e32 v77, v13
	v_add_f32_e32 v136, v76, v136
	v_exp_f32_e32 v78, v14
	v_mfma_f32_32x32x16_bf16 v[48:63], v[240:243], v[116:119], v[48:63]
	ds_read_b128 v[188:191], v249 offset:28672
	v_add_f32_e32 v136, v77, v136
	v_exp_f32_e32 v79, v15
	v_add_f32_e32 v136, v78, v136
	s_nop 0
	v_add_f32_e32 v134, v79, v136
	v_cmp_nge_f32_e32 vcc, s65, v134
	v_cmp_gt_f32_e64 s[0:1], s72, v134
	s_or_b64 vcc, vcc, s[0:1]
	s_cbranch_vccnz .Lat_rare2

.Lat_stab4_ret:
	v_mfma_f32_32x32x16_bf16 v[16:31], v[224:227], v[96:99], 0
	ds_read_b128 v[208:211], v244 offset:49152
	v_cvt_pk_bf16_f32 v112, v80, v81
	v_cvt_pk_bf16_f32 v113, v82, v83
	v_cvt_pk_bf16_f32 v114, v84, v85
	v_cvt_pk_bf16_f32 v115, v86, v87
	v_cvt_pk_bf16_f32 v116, v88, v89
	s_add_i32 m0, s83, 0
	s_nop 0
	global_load_lds_dwordx4 v252, s[78:79]
	v_mfma_f32_32x32x16_bf16 v[16:31], v[228:231], v[100:103], v[16:31]
	ds_read_b128 v[212:215], v245 offset:49152
	v_cvt_pk_bf16_f32 v117, v90, v91
	v_cvt_pk_bf16_f32 v118, v92, v93
	v_cvt_pk_bf16_f32 v119, v94, v95
	v_exp_f32_e32 v64, v0
	v_exp_f32_e32 v65, v1
	global_load_lds_dwordx4 v253, s[78:79] offset:1024
	s_add_i32 m0, s83, 8192
	s_nop 0
	v_mfma_f32_32x32x16_bf16 v[16:31], v[232:235], v[104:107], v[16:31]
	ds_read_b128 v[216:219], v246 offset:49152
	v_exp_f32_e32 v66, v2
	v_add_f32_e32 v136, v64, v65
	v_exp_f32_e32 v67, v3
	v_add_f32_e32 v136, v66, v136
	v_exp_f32_e32 v68, v4
	global_load_lds_dwordx4 v254, s[80:81]
	s_add_u32 s78, s78, 0x2000
	s_addc_u32 s79, s79, 0
	v_mfma_f32_32x32x16_bf16 v[16:31], v[236:239], v[108:111], v[16:31]
	ds_read_b128 v[220:223], v247 offset:49152
	v_add_f32_e32 v136, v67, v136
	v_exp_f32_e32 v69, v5
	v_add_f32_e32 v136, v68, v136
	v_exp_f32_e32 v70, v6
	v_add_f32_e32 v136, v69, v136
	global_load_lds_dwordx4 v255, s[80:81] offset:1024
	s_add_u32 s80, s80, 0x80
	s_addc_u32 s81, s81, 0
	s_waitcnt lgkmcnt(4)
	v_mfma_f32_32x32x16_bf16 v[32:47], v[192:195], v[112:115], v[32:47]
	ds_read_b128 v[176:179], v248 offset:40960
	v_exp_f32_e32 v71, v7
	v_add_f32_e32 v136, v70, v136
	v_exp_f32_e32 v72, v8
	v_add_f32_e32 v136, v71, v136
	v_exp_f32_e32 v73, v9
	v_mfma_f32_32x32x16_bf16 v[48:63], v[196:199], v[112:115], v[48:63]
	ds_read_b128 v[180:183], v248 offset:45056
	v_add_f32_e32 v136, v72, v136
	v_exp_f32_e32 v74, v10
	v_add_f32_e32 v136, v73, v136
	v_exp_f32_e32 v75, v11
	v_add_f32_e32 v136, v74, v136
	v_mfma_f32_32x32x16_bf16 v[32:47], v[200:203], v[116:119], v[32:47]
	ds_read_b128 v[184:187], v249 offset:40960
	v_exp_f32_e32 v76, v12
	v_add_f32_e32 v136, v75, v136
	v_exp_f32_e32 v77, v13
	v_add_f32_e32 v136, v76, v136
	v_exp_f32_e32 v78, v14
	v_mfma_f32_32x32x16_bf16 v[48:63], v[240:243], v[116:119], v[48:63]
	ds_read_b128 v[188:191], v249 offset:45056
	v_add_f32_e32 v136, v77, v136
	v_exp_f32_e32 v79, v15
	v_add_f32_e32 v136, v78, v136
	s_nop 0
	v_add_f32_e32 v134, v79, v136
	v_cmp_nge_f32_e32 vcc, s65, v134
	v_cmp_gt_f32_e64 s[0:1], s72, v134
	s_or_b64 vcc, vcc, s[0:1]
	s_cbranch_vccnz .Lat_rare4

.Lat_stab6_ret:
	v_mfma_f32_32x32x16_bf16 v[16:31], v[224:227], v[96:99], 0
	ds_read_b128 v[208:211], v244 offset:0
	v_cvt_pk_bf16_f32 v112, v80, v81
	v_cvt_pk_bf16_f32 v113, v82, v83
	v_cvt_pk_bf16_f32 v114, v84, v85
	v_cvt_pk_bf16_f32 v115, v86, v87
	v_cvt_pk_bf16_f32 v116, v88, v89
	s_add_i32 m0, s83, 16384
	s_nop 0
	global_load_lds_dwordx4 v252, s[78:79]
	v_mfma_f32_32x32x16_bf16 v[16:31], v[228:231], v[100:103], v[16:31]
	ds_read_b128 v[212:215], v245 offset:0
	v_cvt_pk_bf16_f32 v117, v90, v91
	v_cvt_pk_bf16_f32 v118, v92, v93
	v_cvt_pk_bf16_f32 v119, v94, v95
	v_exp_f32_e32 v64, v0
	v_exp_f32_e32 v65, v1
	global_load_lds_dwordx4 v253, s[78:79] offset:1024
	s_add_i32 m0, s83, 24576
	s_nop 0
	v_mfma_f32_32x32x16_bf16 v[16:31], v[232:235], v[104:107], v[16:31]
	ds_read_b128 v[216:219], v246 offset:0
	v_exp_f32_e32 v66, v2
	v_add_f32_e32 v136, v64, v65
	v_exp_f32_e32 v67, v3
	v_add_f32_e32 v136, v66, v136
	v_exp_f32_e32 v68, v4
	global_load_lds_dwordx4 v254, s[80:81]
	s_add_u32 s78, s78, 0x2000
	s_addc_u32 s79, s79, 0
	v_mfma_f32_32x32x16_bf16 v[16:31], v[236:239], v[108:111], v[16:31]
	ds_read_b128 v[220:223], v247 offset:0
	v_add_f32_e32 v136, v67, v136
	v_exp_f32_e32 v69, v5
	v_add_f32_e32 v136, v68, v136
	v_exp_f32_e32 v70, v6
	v_add_f32_e32 v136, v69, v136
	global_load_lds_dwordx4 v255, s[80:81] offset:1024
	s_add_u32 s80, s80, 0x80
	s_addc_u32 s81, s81, 0
	s_waitcnt lgkmcnt(4)
	v_mfma_f32_32x32x16_bf16 v[32:47], v[192:195], v[112:115], v[32:47]
	ds_read_b128 v[176:179], v248 offset:57344
	v_exp_f32_e32 v71, v7
	v_add_f32_e32 v136, v70, v136
	v_exp_f32_e32 v72, v8
	v_add_f32_e32 v136, v71, v136
	v_exp_f32_e32 v73, v9
	v_mfma_f32_32x32x16_bf16 v[48:63], v[196:199], v[112:115], v[48:63]
	ds_read_b128 v[180:183], v248 offset:61440
	v_add_f32_e32 v136, v72, v136
	v_exp_f32_e32 v74, v10
	v_add_f32_e32 v136, v73, v136
	v_exp_f32_e32 v75, v11
	v_add_f32_e32 v136, v74, v136
	v_mfma_f32_32x32x16_bf16 v[32:47], v[200:203], v[116:119], v[32:47]
	ds_read_b128 v[184:187], v249 offset:57344
	v_exp_f32_e32 v76, v12
	v_add_f32_e32 v136, v75, v136
	v_exp_f32_e32 v77, v13
	v_add_f32_e32 v136, v76, v136
	v_exp_f32_e32 v78, v14
	v_mfma_f32_32x32x16_bf16 v[48:63], v[240:243], v[116:119], v[48:63]
	ds_read_b128 v[188:191], v249 offset:61440
	v_add_f32_e32 v136, v77, v136
	v_exp_f32_e32 v79, v15
	v_add_f32_e32 v136, v78, v136
	s_nop 0
	v_add_f32_e32 v134, v79, v136
	v_cmp_nge_f32_e32 vcc, s65, v134
	v_cmp_gt_f32_e64 s[0:1], s72, v134
	s_or_b64 vcc, vcc, s[0:1]
	s_cbranch_vccnz .Lat_rare6
